# up K-loop: B-operand (weight tile) LDS-DMA loads with nt so the re-used A (XB) tiles stay in L2 (test, on top of v70)
# baseline (speedup 1.0000x reference)
; #define PG8_STAGE(bufoff, gbase, voff) do { _Pragma("unroll") for (int _i = 0; _i < 2; ++_i) \
;         __builtin_amdgcn_global_load_lds((const unsigned*)((const char*)(gbase) + (voff)[_i]), (PG8_LAS unsigned*)(lds + (bufoff) + ldsw + _i * 8192), 16, 0, 0); } while (0)
; #define PG8_LDA(dst, b, h) do { _Pragma("unroll") for (int m = 0; m < 4; ++m) _Pragma("unroll") for (int k = 0; k < 2; ++k) dst[m][k] = *(const PG8_LAS bf16x8*)(lds + PG8_SA(b, h) + aoff + m * 2048 + k * 1024); } while (0)
; #define PG8_LDB(dst, b, h) do { _Pragma("unroll") for (int n = 0; n < 2; ++n) _Pragma("unroll") for (int k = 0; k < 2; ++k) dst[n][k] = *(const PG8_LAS bf16x8*)(lds + PG8_SB(b, h) + boff + n * 2048 + k * 1024); } while (0)
; #define PG8_MMA(ai, bj, At, Bt) do { __builtin_amdgcn_s_setprio(1); _Pragma("unroll") for (int m = 0; m < 4; ++m) _Pragma("unroll") for (int n = 0; n < 2; ++n) _Pragma("unroll") for (int k = 0; k < 2; ++k) \
;         acc[ai][bj][m][n] = __builtin_amdgcn_mfma_f32_16x16x32_bf16(Bt[n][k], At[m][k], acc[ai][bj][m][n], 0, 0, 0); __builtin_amdgcn_s_setprio(0); } while (0)
; #define PG8_WAIT_V(n) asm volatile("s_waitcnt vmcnt(" #n ")" ::: "memory")
; #define PG8_WAIT_L(n) asm volatile("s_waitcnt lgkmcnt(" #n ")" ::: "memory")
; #define PG8_BAR __builtin_amdgcn_s_barrier()
; #define PG8_SCHED __builtin_amdgcn_sched_barrier(0)
; template <class Epi, class Sched, bool ALIGN_EPI = false, bool SP2 = false>
; __device__ __forceinline__ void gemm_phase(PG8_LAS unsigned char* lds, const Gemm g, const Sched& S, const Epi& E) {
;     ...
;             PG8_LDB(B0, 0, 0); PG8_LDB(B1, 0, 1); PG8_SCHED; PG8_LDA(At, 0, 0); PG8_STAGE(PG8_SA(1, 1), a1 + hstep, voffA);
;             PG8_WAIT_V(8); PG8_WAIT_L(0); PG8_BAR; PG8_MMA(0, 0, At, B0); PG8_MMA(0, 1, At, B1); PG8_BAR; PG8_SCHED;
;             PG8_LDA(At, 0, 1); PG8_STAGE(PG8_SB(0, 0), b2, voffB); PG8_STAGE(PG8_SB(0, 1), b2 + hstep, voffB); PG8_STAGE(PG8_SA(0, 0), a2, voffA);
;             PG8_WAIT_V(8); PG8_WAIT_L(0); PG8_BAR; PG8_MMA(1, 0, At, B0); PG8_MMA(1, 1, At, B1); PG8_BAR; PG8_SCHED;
.Lup_peel:
	ds_read_b128 v[140:143], v254
	ds_read_b128 v[168:171], v254 offset:1024
	ds_read_b128 v[172:175], v254 offset:2048
	ds_read_b128 v[176:179], v254 offset:3072
	ds_read_b128 v[180:183], v254 offset:16384
	ds_read_b128 v[184:187], v254 offset:17408
	ds_read_b128 v[188:191], v254 offset:18432
	ds_read_b128 v[210:213], v254 offset:19456
	s_add_u32 s16, s14, 0xfffc0080
	s_addc_u32 s17, s15, -1
	s_cmp_eq_u32 s53, 12
	s_cselect_b32 s19, s7, s17
	s_cselect_b32 s18, s49, s16
	s_cselect_b32 s17, s5, s52
	s_cselect_b32 s16, s50, s51
	s_mov_b32 m0, s43
	ds_read_b128 v[214:217], v165
	ds_read_b128 v[218:221], v165 offset:1024
	ds_read_b128 v[222:225], v165 offset:2048
	ds_read_b128 v[226:229], v165 offset:3072
	ds_read_b128 v[230:233], v165 offset:4096
	ds_read_b128 v[234:237], v165 offset:5120
	ds_read_b128 v[238:241], v165 offset:6144
	ds_read_b128 v[242:245], v165 offset:7168
	global_load_lds_dwordx4 v136, s[14:15]
	s_mov_b32 m0, s44
	s_nop 0
	global_load_lds_dwordx4 v138, s[14:15]
	s_waitcnt vmcnt(8)
	s_waitcnt lgkmcnt(0)
	s_barrier
	s_setprio 1
	v_mfma_f32_16x16x32_bf16 v[124:127], v[140:143], v[214:217], 0
	v_mfma_f32_16x16x32_bf16 v[116:119], v[172:175], v[214:217], 0
	v_mfma_f32_16x16x32_bf16 v[108:111], v[140:143], v[222:225], 0
	v_mfma_f32_16x16x32_bf16 v[100:103], v[172:175], v[222:225], 0
	v_mfma_f32_16x16x32_bf16 v[92:95], v[140:143], v[230:233], 0
	v_mfma_f32_16x16x32_bf16 v[84:87], v[172:175], v[230:233], 0
	v_mfma_f32_16x16x32_bf16 v[76:79], v[140:143], v[238:241], 0
	v_mfma_f32_16x16x32_bf16 v[68:71], v[172:175], v[238:241], 0
	v_mfma_f32_16x16x32_bf16 v[124:127], v[168:171], v[218:221], v[124:127]
	v_mfma_f32_16x16x32_bf16 v[116:119], v[176:179], v[218:221], v[116:119]
	v_mfma_f32_16x16x32_bf16 v[108:111], v[168:171], v[226:229], v[108:111]
	v_mfma_f32_16x16x32_bf16 v[100:103], v[176:179], v[226:229], v[100:103]
	v_mfma_f32_16x16x32_bf16 v[92:95], v[168:171], v[234:237], v[92:95]
	v_mfma_f32_16x16x32_bf16 v[84:87], v[176:179], v[234:237], v[84:87]
	v_mfma_f32_16x16x32_bf16 v[76:79], v[168:171], v[242:245], v[76:79]
	v_mfma_f32_16x16x32_bf16 v[68:71], v[176:179], v[242:245], v[68:71]
	v_mfma_f32_16x16x32_bf16 v[120:123], v[180:183], v[214:217], 0
	v_mfma_f32_16x16x32_bf16 v[112:115], v[188:191], v[214:217], 0
	v_mfma_f32_16x16x32_bf16 v[104:107], v[180:183], v[222:225], 0
	v_mfma_f32_16x16x32_bf16 v[96:99], v[188:191], v[222:225], 0
	v_mfma_f32_16x16x32_bf16 v[88:91], v[180:183], v[230:233], 0
	v_mfma_f32_16x16x32_bf16 v[80:83], v[188:191], v[230:233], 0
	v_mfma_f32_16x16x32_bf16 v[72:75], v[180:183], v[238:241], 0
	v_mfma_f32_16x16x32_bf16 v[64:67], v[188:191], v[238:241], 0
	v_mfma_f32_16x16x32_bf16 v[120:123], v[184:187], v[218:221], v[120:123]
	v_mfma_f32_16x16x32_bf16 v[112:115], v[210:213], v[218:221], v[112:115]
	v_mfma_f32_16x16x32_bf16 v[104:107], v[184:187], v[226:229], v[104:107]
	v_mfma_f32_16x16x32_bf16 v[96:99], v[210:213], v[226:229], v[96:99]
	v_mfma_f32_16x16x32_bf16 v[88:91], v[184:187], v[234:237], v[88:91]
	v_mfma_f32_16x16x32_bf16 v[80:83], v[210:213], v[234:237], v[80:83]
	v_mfma_f32_16x16x32_bf16 v[72:75], v[184:187], v[242:245], v[72:75]
	v_mfma_f32_16x16x32_bf16 v[64:67], v[210:213], v[242:245], v[64:67]
	s_setprio 0
	s_barrier
	s_mov_b32 m0, s27
	s_add_u32 s54, s16, 0x40000
	s_addc_u32 s55, s17, 0
	ds_read_b128 v[214:217], v165 offset:16384
	ds_read_b128 v[218:221], v165 offset:17408
	ds_read_b128 v[222:225], v165 offset:18432
	ds_read_b128 v[226:229], v165 offset:19456
	ds_read_b128 v[230:233], v165 offset:20480
	ds_read_b128 v[234:237], v165 offset:21504
	ds_read_b128 v[238:241], v165 offset:22528
	ds_read_b128 v[242:245], v165 offset:23552
	global_load_lds_dwordx4 v132, s[16:17] nt
	s_mov_b32 m0, s28
	s_nop 0
	global_load_lds_dwordx4 v128, s[16:17] nt
	s_mov_b32 m0, s29
	s_nop 0
	global_load_lds_dwordx4 v132, s[54:55] nt
	s_mov_b32 m0, s30
	s_nop 0
	global_load_lds_dwordx4 v128, s[54:55] nt
	s_mov_b32 m0, s22
	s_nop 0
	global_load_lds_dwordx4 v134, s[18:19]
	s_mov_b32 m0, s31
	s_nop 0
	global_load_lds_dwordx4 v130, s[18:19]
	s_waitcnt vmcnt(8)
	s_waitcnt lgkmcnt(0)
	s_barrier
	s_setprio 1
	v_mfma_f32_16x16x32_bf16 v[60:63], v[140:143], v[214:217], 0
	v_mfma_f32_16x16x32_bf16 v[52:55], v[172:175], v[214:217], 0
	v_mfma_f32_16x16x32_bf16 v[44:47], v[140:143], v[222:225], 0
	v_mfma_f32_16x16x32_bf16 v[36:39], v[172:175], v[222:225], 0
	v_mfma_f32_16x16x32_bf16 v[28:31], v[140:143], v[230:233], 0
	v_mfma_f32_16x16x32_bf16 v[20:23], v[172:175], v[230:233], 0
	v_mfma_f32_16x16x32_bf16 v[12:15], v[140:143], v[238:241], 0
	v_mfma_f32_16x16x32_bf16 v[4:7], v[172:175], v[238:241], 0
	v_mfma_f32_16x16x32_bf16 v[60:63], v[168:171], v[218:221], v[60:63]
	v_mfma_f32_16x16x32_bf16 v[52:55], v[176:179], v[218:221], v[52:55]
	v_mfma_f32_16x16x32_bf16 v[44:47], v[168:171], v[226:229], v[44:47]
	v_mfma_f32_16x16x32_bf16 v[36:39], v[176:179], v[226:229], v[36:39]
	v_mfma_f32_16x16x32_bf16 v[28:31], v[168:171], v[234:237], v[28:31]
	v_mfma_f32_16x16x32_bf16 v[20:23], v[176:179], v[234:237], v[20:23]
	v_mfma_f32_16x16x32_bf16 v[12:15], v[168:171], v[242:245], v[12:15]
	v_mfma_f32_16x16x32_bf16 v[4:7], v[176:179], v[242:245], v[4:7]
	v_mfma_f32_16x16x32_bf16 v[56:59], v[180:183], v[214:217], 0
	v_mfma_f32_16x16x32_bf16 v[48:51], v[188:191], v[214:217], 0
	v_mfma_f32_16x16x32_bf16 v[40:43], v[180:183], v[222:225], 0
	v_mfma_f32_16x16x32_bf16 v[32:35], v[188:191], v[222:225], 0
	v_mfma_f32_16x16x32_bf16 v[24:27], v[180:183], v[230:233], 0
	v_mfma_f32_16x16x32_bf16 v[16:19], v[188:191], v[230:233], 0
	v_mfma_f32_16x16x32_bf16 v[8:11], v[180:183], v[238:241], 0
	v_mfma_f32_16x16x32_bf16 v[0:3], v[188:191], v[238:241], 0
	v_mfma_f32_16x16x32_bf16 v[56:59], v[184:187], v[218:221], v[56:59]
	v_mfma_f32_16x16x32_bf16 v[48:51], v[210:213], v[218:221], v[48:51]
	v_mfma_f32_16x16x32_bf16 v[40:43], v[184:187], v[226:229], v[40:43]
	v_mfma_f32_16x16x32_bf16 v[32:35], v[210:213], v[226:229], v[32:35]
	v_mfma_f32_16x16x32_bf16 v[24:27], v[184:187], v[234:237], v[24:27]
	v_mfma_f32_16x16x32_bf16 v[16:19], v[210:213], v[234:237], v[16:19]
	v_mfma_f32_16x16x32_bf16 v[8:11], v[184:187], v[242:245], v[8:11]
	v_mfma_f32_16x16x32_bf16 v[0:3], v[210:213], v[242:245], v[0:3]
	s_setprio 0
	s_barrier
; #define PG8_STAGE(bufoff, gbase, voff) do { _Pragma("unroll") for (int _i = 0; _i < 2; ++_i) \
;         __builtin_amdgcn_global_load_lds((const unsigned*)((const char*)(gbase) + (voff)[_i]), (PG8_LAS unsigned*)(lds + (bufoff) + ldsw + _i * 8192), 16, 0, 0); } while (0)
; #define PG8_LDA(dst, b, h) do { _Pragma("unroll") for (int m = 0; m < 4; ++m) _Pragma("unroll") for (int k = 0; k < 2; ++k) dst[m][k] = *(const PG8_LAS bf16x8*)(lds + PG8_SA(b, h) + aoff + m * 2048 + k * 1024); } while (0)
; #define PG8_LDB(dst, b, h) do { _Pragma("unroll") for (int n = 0; n < 2; ++n) _Pragma("unroll") for (int k = 0; k < 2; ++k) dst[n][k] = *(const PG8_LAS bf16x8*)(lds + PG8_SB(b, h) + boff + n * 2048 + k * 1024); } while (0)
; #define PG8_MMA(ai, bj, At, Bt) do { __builtin_amdgcn_s_setprio(1); _Pragma("unroll") for (int m = 0; m < 4; ++m) _Pragma("unroll") for (int n = 0; n < 2; ++n) _Pragma("unroll") for (int k = 0; k < 2; ++k) \
;         acc[ai][bj][m][n] = __builtin_amdgcn_mfma_f32_16x16x32_bf16(Bt[n][k], At[m][k], acc[ai][bj][m][n], 0, 0, 0); __builtin_amdgcn_s_setprio(0); } while (0)
; #define PG8_WAIT_V(n) asm volatile("s_waitcnt vmcnt(" #n ")" ::: "memory")
; #define PG8_WAIT_L(n) asm volatile("s_waitcnt lgkmcnt(" #n ")" ::: "memory")
; #define PG8_BAR __builtin_amdgcn_s_barrier()
; #define PG8_SCHED __builtin_amdgcn_sched_barrier(0)
; template <class Epi, class Sched, bool ALIGN_EPI = false, bool SP2 = false>
; __device__ __forceinline__ void gemm_phase(PG8_LAS unsigned char* lds, const Gemm g, const Sched& S, const Epi& E) {
;     ...
;             PG8_LDB(B0, 1, 0); PG8_LDB(B1, 1, 1); PG8_SCHED; PG8_LDA(At, 1, 0); PG8_STAGE(PG8_SA(0, 1), a2 + hstep, voffA);
;             PG8_WAIT_V(8); PG8_WAIT_L(0); PG8_BAR; PG8_MMA(0, 0, At, B0); PG8_MMA(0, 1, At, B1); PG8_BAR; PG8_SCHED;
;             PG8_LDA(At, 1, 1); PG8_STAGE(PG8_SB(1, 0), b3, voffB); PG8_STAGE(PG8_SB(1, 1), b3 + hstep, voffB); PG8_STAGE(PG8_SA(1, 0), a3, voffA);
;             PG8_WAIT_V(8); PG8_WAIT_L(0); PG8_BAR; PG8_MMA(1, 0, At, B0); PG8_MMA(1, 1, At, B1); PG8_BAR; PG8_SCHED;
	ds_read_b128 v[140:143], v254 offset:32768
	ds_read_b128 v[168:171], v254 offset:33792
	ds_read_b128 v[172:175], v254 offset:34816
	ds_read_b128 v[176:179], v254 offset:35840
	ds_read_b128 v[180:183], v254 offset:49152
	ds_read_b128 v[184:187], v254 offset:50176
	ds_read_b128 v[188:191], v254 offset:51200
	ds_read_b128 v[210:213], v254 offset:52224
	s_add_u32 s18, s18, 0x40000
	s_addc_u32 s19, s19, 0
	s_mov_b32 m0, s33
	ds_read_b128 v[214:217], v165 offset:32768
	ds_read_b128 v[218:221], v165 offset:33792
	ds_read_b128 v[222:225], v165 offset:34816
	ds_read_b128 v[226:229], v165 offset:35840
	ds_read_b128 v[230:233], v165 offset:36864
	ds_read_b128 v[234:237], v165 offset:37888
	ds_read_b128 v[238:241], v165 offset:38912
	ds_read_b128 v[242:245], v165 offset:39936
	global_load_lds_dwordx4 v134, s[18:19]
	s_mov_b32 m0, s34
	s_nop 0
	global_load_lds_dwordx4 v130, s[18:19]
	s_waitcnt vmcnt(8)
	s_waitcnt lgkmcnt(0)
	s_barrier
	s_setprio 1
	v_mfma_f32_16x16x32_bf16 v[124:127], v[140:143], v[214:217], v[124:127]
	v_mfma_f32_16x16x32_bf16 v[116:119], v[172:175], v[214:217], v[116:119]
	v_mfma_f32_16x16x32_bf16 v[108:111], v[140:143], v[222:225], v[108:111]
	v_mfma_f32_16x16x32_bf16 v[100:103], v[172:175], v[222:225], v[100:103]
	v_mfma_f32_16x16x32_bf16 v[92:95], v[140:143], v[230:233], v[92:95]
	v_mfma_f32_16x16x32_bf16 v[84:87], v[172:175], v[230:233], v[84:87]
	v_mfma_f32_16x16x32_bf16 v[76:79], v[140:143], v[238:241], v[76:79]
	v_mfma_f32_16x16x32_bf16 v[68:71], v[172:175], v[238:241], v[68:71]
	v_mfma_f32_16x16x32_bf16 v[124:127], v[168:171], v[218:221], v[124:127]
	v_mfma_f32_16x16x32_bf16 v[116:119], v[176:179], v[218:221], v[116:119]
	v_mfma_f32_16x16x32_bf16 v[108:111], v[168:171], v[226:229], v[108:111]
	v_mfma_f32_16x16x32_bf16 v[100:103], v[176:179], v[226:229], v[100:103]
	v_mfma_f32_16x16x32_bf16 v[92:95], v[168:171], v[234:237], v[92:95]
	v_mfma_f32_16x16x32_bf16 v[84:87], v[176:179], v[234:237], v[84:87]
	v_mfma_f32_16x16x32_bf16 v[76:79], v[168:171], v[242:245], v[76:79]
	v_mfma_f32_16x16x32_bf16 v[68:71], v[176:179], v[242:245], v[68:71]
	v_mfma_f32_16x16x32_bf16 v[120:123], v[180:183], v[214:217], v[120:123]
	v_mfma_f32_16x16x32_bf16 v[112:115], v[188:191], v[214:217], v[112:115]
	v_mfma_f32_16x16x32_bf16 v[104:107], v[180:183], v[222:225], v[104:107]
	v_mfma_f32_16x16x32_bf16 v[96:99], v[188:191], v[222:225], v[96:99]
	v_mfma_f32_16x16x32_bf16 v[88:91], v[180:183], v[230:233], v[88:91]
	v_mfma_f32_16x16x32_bf16 v[80:83], v[188:191], v[230:233], v[80:83]
	v_mfma_f32_16x16x32_bf16 v[72:75], v[180:183], v[238:241], v[72:75]
	v_mfma_f32_16x16x32_bf16 v[64:67], v[188:191], v[238:241], v[64:67]
	v_mfma_f32_16x16x32_bf16 v[120:123], v[184:187], v[218:221], v[120:123]
	v_mfma_f32_16x16x32_bf16 v[112:115], v[210:213], v[218:221], v[112:115]
	v_mfma_f32_16x16x32_bf16 v[104:107], v[184:187], v[226:229], v[104:107]
	v_mfma_f32_16x16x32_bf16 v[96:99], v[210:213], v[226:229], v[96:99]
	v_mfma_f32_16x16x32_bf16 v[88:91], v[184:187], v[234:237], v[88:91]
	v_mfma_f32_16x16x32_bf16 v[80:83], v[210:213], v[234:237], v[80:83]
	v_mfma_f32_16x16x32_bf16 v[72:75], v[184:187], v[242:245], v[72:75]
	v_mfma_f32_16x16x32_bf16 v[64:67], v[210:213], v[242:245], v[64:67]
	s_setprio 0
	s_barrier
	s_mov_b32 m0, s37
	s_add_u32 s16, s16, 0x40080
	s_addc_u32 s17, s17, 0
	ds_read_b128 v[214:217], v165 offset:49152
	ds_read_b128 v[218:221], v165 offset:50176
	ds_read_b128 v[222:225], v165 offset:51200
	ds_read_b128 v[226:229], v165 offset:52224
	ds_read_b128 v[230:233], v165 offset:53248
	ds_read_b128 v[234:237], v165 offset:54272
	ds_read_b128 v[238:241], v165 offset:55296
	ds_read_b128 v[242:245], v165 offset:56320
	s_add_u32 s98, s16, 0xfffc0000
	s_addc_u32 s99, s17, -1
	global_load_lds_dwordx4 v132, s[98:99] nt
	s_mov_b32 m0, s38
	s_nop 0
	global_load_lds_dwordx4 v128, s[98:99] nt
	s_mov_b32 m0, s41
	s_nop 0
	global_load_lds_dwordx4 v132, s[16:17] nt
	s_mov_b32 m0, s42
	s_nop 0
	global_load_lds_dwordx4 v128, s[16:17] nt
	s_mov_b32 m0, s39
	s_nop 0
	s_add_u32 s100, s18, 0xfffc0080
	s_addc_u32 s101, s19, -1
	global_load_lds_dwordx4 v134, s[100:101]
	s_mov_b32 m0, s40
	s_nop 0
	global_load_lds_dwordx4 v130, s[100:101]
	s_waitcnt vmcnt(8)
	s_waitcnt lgkmcnt(0)
	s_barrier
	s_setprio 1
	v_mfma_f32_16x16x32_bf16 v[60:63], v[140:143], v[214:217], v[60:63]
	v_mfma_f32_16x16x32_bf16 v[52:55], v[172:175], v[214:217], v[52:55]
	v_mfma_f32_16x16x32_bf16 v[44:47], v[140:143], v[222:225], v[44:47]
	v_mfma_f32_16x16x32_bf16 v[36:39], v[172:175], v[222:225], v[36:39]
	v_mfma_f32_16x16x32_bf16 v[28:31], v[140:143], v[230:233], v[28:31]
	v_mfma_f32_16x16x32_bf16 v[20:23], v[172:175], v[230:233], v[20:23]
	v_mfma_f32_16x16x32_bf16 v[12:15], v[140:143], v[238:241], v[12:15]
	v_mfma_f32_16x16x32_bf16 v[4:7], v[172:175], v[238:241], v[4:7]
	v_mfma_f32_16x16x32_bf16 v[60:63], v[168:171], v[218:221], v[60:63]
	v_mfma_f32_16x16x32_bf16 v[52:55], v[176:179], v[218:221], v[52:55]
	v_mfma_f32_16x16x32_bf16 v[44:47], v[168:171], v[226:229], v[44:47]
	v_mfma_f32_16x16x32_bf16 v[36:39], v[176:179], v[226:229], v[36:39]
	v_mfma_f32_16x16x32_bf16 v[28:31], v[168:171], v[234:237], v[28:31]
	v_mfma_f32_16x16x32_bf16 v[20:23], v[176:179], v[234:237], v[20:23]
	v_mfma_f32_16x16x32_bf16 v[12:15], v[168:171], v[242:245], v[12:15]
	v_mfma_f32_16x16x32_bf16 v[4:7], v[176:179], v[242:245], v[4:7]
	v_mfma_f32_16x16x32_bf16 v[56:59], v[180:183], v[214:217], v[56:59]
	v_mfma_f32_16x16x32_bf16 v[48:51], v[188:191], v[214:217], v[48:51]
	v_mfma_f32_16x16x32_bf16 v[40:43], v[180:183], v[222:225], v[40:43]
	v_mfma_f32_16x16x32_bf16 v[32:35], v[188:191], v[222:225], v[32:35]
	v_mfma_f32_16x16x32_bf16 v[24:27], v[180:183], v[230:233], v[24:27]
	v_mfma_f32_16x16x32_bf16 v[16:19], v[188:191], v[230:233], v[16:19]
	v_mfma_f32_16x16x32_bf16 v[8:11], v[180:183], v[238:241], v[8:11]
	v_mfma_f32_16x16x32_bf16 v[0:3], v[188:191], v[238:241], v[0:3]
	v_mfma_f32_16x16x32_bf16 v[56:59], v[184:187], v[218:221], v[56:59]
	v_mfma_f32_16x16x32_bf16 v[48:51], v[210:213], v[218:221], v[48:51]
	v_mfma_f32_16x16x32_bf16 v[40:43], v[184:187], v[226:229], v[40:43]
	v_mfma_f32_16x16x32_bf16 v[32:35], v[210:213], v[226:229], v[32:35]
	v_mfma_f32_16x16x32_bf16 v[24:27], v[184:187], v[234:237], v[24:27]
	v_mfma_f32_16x16x32_bf16 v[16:19], v[210:213], v[234:237], v[16:19]
	v_mfma_f32_16x16x32_bf16 v[8:11], v[184:187], v[242:245], v[8:11]
	v_mfma_f32_16x16x32_bf16 v[0:3], v[210:213], v[242:245], v[0:3]
	s_setprio 0
	s_barrier
	s_add_i32 s53, s53, 2
	s_add_u32 s14, s14, 0x100
	s_addc_u32 s15, s15, 0
	s_add_u32 s51, s51, 0x100
	s_addc_u32 s52, s52, 0
	s_cmp_gt_u32 s53, 13
; #define PG8_STAGE(bufoff, gbase, voff) do { _Pragma("unroll") for (int _i = 0; _i < 2; ++_i) \
;         __builtin_amdgcn_global_load_lds((const unsigned*)((const char*)(gbase) + (voff)[_i]), (PG8_LAS unsigned*)(lds + (bufoff) + ldsw + _i * 8192), 16, 0, 0); } while (0)
; #define PG8_LDA(dst, b, h) do { _Pragma("unroll") for (int m = 0; m < 4; ++m) _Pragma("unroll") for (int k = 0; k < 2; ++k) dst[m][k] = *(const PG8_LAS bf16x8*)(lds + PG8_SA(b, h) + aoff + m * 2048 + k * 1024); } while (0)
; #define PG8_LDB(dst, b, h) do { _Pragma("unroll") for (int n = 0; n < 2; ++n) _Pragma("unroll") for (int k = 0; k < 2; ++k) dst[n][k] = *(const PG8_LAS bf16x8*)(lds + PG8_SB(b, h) + boff + n * 2048 + k * 1024); } while (0)
; #define PG8_MMA(ai, bj, At, Bt) do { __builtin_amdgcn_s_setprio(1); _Pragma("unroll") for (int m = 0; m < 4; ++m) _Pragma("unroll") for (int n = 0; n < 2; ++n) _Pragma("unroll") for (int k = 0; k < 2; ++k) \
;         acc[ai][bj][m][n] = __builtin_amdgcn_mfma_f32_16x16x32_bf16(Bt[n][k], At[m][k], acc[ai][bj][m][n], 0, 0, 0); __builtin_amdgcn_s_setprio(0); } while (0)
; #define PG8_WAIT_V(n) asm volatile("s_waitcnt vmcnt(" #n ")" ::: "memory")
; #define PG8_WAIT_L(n) asm volatile("s_waitcnt lgkmcnt(" #n ")" ::: "memory")
; #define PG8_BAR __builtin_amdgcn_s_barrier()
; template <class Epi, class Sched, bool ALIGN_EPI = false, bool SP2 = false>
; __device__ __forceinline__ void gemm_phase(PG8_LAS unsigned char* lds, const Gemm g, const Sched& S, const Epi& E) {
;     ...
;             const char* a1 = cA + (size_t)(t + 1) * kstep;
;             const char* a2 = last ? nA : cA + (size_t)(t + 2) * kstep; const char* b2 = last ? nB : cB + (size_t)(t + 2) * kstep;
;             const char* a3 = a2 + kstep; const char* b3 = b2 + kstep;
;             if (last && has_next) S.a_ready(nxt);
;             if constexpr (SP2) {
;             PG8_LDB(B0, 0, 0); PG8_LDB(B1, 0, 1); PG8_SCHED; PG8_LDA(At, 0, 0); PG8_STAGE(PG8_SA(1, 1), a1 + hstep, voffA);
;             PG8_WAIT_V(8); PG8_WAIT_L(0); PG8_BAR; PG8_MMA(0, 0, At, B0); PG8_MMA(0, 1, At, B1); PG8_BAR; PG8_SCHED;
;             PG8_LDA(At, 0, 1); PG8_STAGE(PG8_SB(0, 0), b2, voffB); PG8_STAGE(PG8_SB(0, 1), b2 + hstep, voffB); PG8_STAGE(PG8_SA(0, 0), a2, voffA);
;             PG8_WAIT_V(8); PG8_WAIT_L(0); PG8_BAR; PG8_MMA(1, 0, At, B0); PG8_MMA(1, 1, At, B1); PG8_BAR; PG8_SCHED;
.LBB0_446:
	ds_read_b128 v[140:143], v254
	ds_read_b128 v[168:171], v254 offset:1024
	ds_read_b128 v[172:175], v254 offset:2048
	ds_read_b128 v[176:179], v254 offset:3072
	ds_read_b128 v[180:183], v254 offset:16384
	ds_read_b128 v[184:187], v254 offset:17408
	ds_read_b128 v[188:191], v254 offset:18432
	ds_read_b128 v[210:213], v254 offset:19456
	s_add_u32 s16, s14, 0xfffc0080
	s_addc_u32 s17, s15, -1
	s_cmp_eq_u32 s53, 12
	s_cselect_b32 s19, s7, s17
	s_cselect_b32 s18, s49, s16
	s_cselect_b32 s17, s5, s52
	s_cselect_b32 s16, s50, s51
	s_mov_b32 m0, s43
	ds_read_b128 v[214:217], v165
	ds_read_b128 v[218:221], v165 offset:1024
	ds_read_b128 v[222:225], v165 offset:2048
	ds_read_b128 v[226:229], v165 offset:3072
	ds_read_b128 v[230:233], v165 offset:4096
	ds_read_b128 v[234:237], v165 offset:5120
	ds_read_b128 v[238:241], v165 offset:6144
	ds_read_b128 v[242:245], v165 offset:7168
	global_load_lds_dwordx4 v136, s[14:15]
	s_mov_b32 m0, s44
	s_nop 0
	global_load_lds_dwordx4 v138, s[14:15]
	s_waitcnt vmcnt(8)
	s_waitcnt lgkmcnt(0)
	s_barrier
	s_setprio 1
	v_mfma_f32_16x16x32_bf16 v[124:127], v[140:143], v[214:217], v[124:127]
	v_mfma_f32_16x16x32_bf16 v[116:119], v[172:175], v[214:217], v[116:119]
	v_mfma_f32_16x16x32_bf16 v[108:111], v[140:143], v[222:225], v[108:111]
	v_mfma_f32_16x16x32_bf16 v[100:103], v[172:175], v[222:225], v[100:103]
	v_mfma_f32_16x16x32_bf16 v[92:95], v[140:143], v[230:233], v[92:95]
	v_mfma_f32_16x16x32_bf16 v[84:87], v[172:175], v[230:233], v[84:87]
	v_mfma_f32_16x16x32_bf16 v[76:79], v[140:143], v[238:241], v[76:79]
	v_mfma_f32_16x16x32_bf16 v[68:71], v[172:175], v[238:241], v[68:71]
	v_mfma_f32_16x16x32_bf16 v[124:127], v[168:171], v[218:221], v[124:127]
	v_mfma_f32_16x16x32_bf16 v[116:119], v[176:179], v[218:221], v[116:119]
	v_mfma_f32_16x16x32_bf16 v[108:111], v[168:171], v[226:229], v[108:111]
	v_mfma_f32_16x16x32_bf16 v[100:103], v[176:179], v[226:229], v[100:103]
	v_mfma_f32_16x16x32_bf16 v[92:95], v[168:171], v[234:237], v[92:95]
	v_mfma_f32_16x16x32_bf16 v[84:87], v[176:179], v[234:237], v[84:87]
	v_mfma_f32_16x16x32_bf16 v[76:79], v[168:171], v[242:245], v[76:79]
	v_mfma_f32_16x16x32_bf16 v[68:71], v[176:179], v[242:245], v[68:71]
	v_mfma_f32_16x16x32_bf16 v[120:123], v[180:183], v[214:217], v[120:123]
	v_mfma_f32_16x16x32_bf16 v[112:115], v[188:191], v[214:217], v[112:115]
	v_mfma_f32_16x16x32_bf16 v[104:107], v[180:183], v[222:225], v[104:107]
	v_mfma_f32_16x16x32_bf16 v[96:99], v[188:191], v[222:225], v[96:99]
	v_mfma_f32_16x16x32_bf16 v[88:91], v[180:183], v[230:233], v[88:91]
	v_mfma_f32_16x16x32_bf16 v[80:83], v[188:191], v[230:233], v[80:83]
	v_mfma_f32_16x16x32_bf16 v[72:75], v[180:183], v[238:241], v[72:75]
	v_mfma_f32_16x16x32_bf16 v[64:67], v[188:191], v[238:241], v[64:67]
	v_mfma_f32_16x16x32_bf16 v[120:123], v[184:187], v[218:221], v[120:123]
	v_mfma_f32_16x16x32_bf16 v[112:115], v[210:213], v[218:221], v[112:115]
	v_mfma_f32_16x16x32_bf16 v[104:107], v[184:187], v[226:229], v[104:107]
	v_mfma_f32_16x16x32_bf16 v[96:99], v[210:213], v[226:229], v[96:99]
	v_mfma_f32_16x16x32_bf16 v[88:91], v[184:187], v[234:237], v[88:91]
	v_mfma_f32_16x16x32_bf16 v[80:83], v[210:213], v[234:237], v[80:83]
	v_mfma_f32_16x16x32_bf16 v[72:75], v[184:187], v[242:245], v[72:75]
	v_mfma_f32_16x16x32_bf16 v[64:67], v[210:213], v[242:245], v[64:67]
	s_setprio 0
	s_barrier
	s_mov_b32 m0, s27
	s_add_u32 s54, s16, 0x40000
	s_addc_u32 s55, s17, 0
	ds_read_b128 v[214:217], v165 offset:16384
	ds_read_b128 v[218:221], v165 offset:17408
	ds_read_b128 v[222:225], v165 offset:18432
	ds_read_b128 v[226:229], v165 offset:19456
	ds_read_b128 v[230:233], v165 offset:20480
	ds_read_b128 v[234:237], v165 offset:21504
	ds_read_b128 v[238:241], v165 offset:22528
	ds_read_b128 v[242:245], v165 offset:23552
	global_load_lds_dwordx4 v132, s[16:17] nt
	s_mov_b32 m0, s28
	s_nop 0
	global_load_lds_dwordx4 v128, s[16:17] nt
	s_mov_b32 m0, s29
	s_nop 0
	global_load_lds_dwordx4 v132, s[54:55] nt
	s_mov_b32 m0, s30
	s_nop 0
	global_load_lds_dwordx4 v128, s[54:55] nt
	s_mov_b32 m0, s22
	s_nop 0
	global_load_lds_dwordx4 v134, s[18:19]
	s_mov_b32 m0, s31
	s_nop 0
	global_load_lds_dwordx4 v130, s[18:19]
	s_waitcnt vmcnt(8)
	s_waitcnt lgkmcnt(0)
	s_barrier
	s_setprio 1
	v_mfma_f32_16x16x32_bf16 v[60:63], v[140:143], v[214:217], v[60:63]
	v_mfma_f32_16x16x32_bf16 v[52:55], v[172:175], v[214:217], v[52:55]
	v_mfma_f32_16x16x32_bf16 v[44:47], v[140:143], v[222:225], v[44:47]
	v_mfma_f32_16x16x32_bf16 v[36:39], v[172:175], v[222:225], v[36:39]
	v_mfma_f32_16x16x32_bf16 v[28:31], v[140:143], v[230:233], v[28:31]
	v_mfma_f32_16x16x32_bf16 v[20:23], v[172:175], v[230:233], v[20:23]
	v_mfma_f32_16x16x32_bf16 v[12:15], v[140:143], v[238:241], v[12:15]
	v_mfma_f32_16x16x32_bf16 v[4:7], v[172:175], v[238:241], v[4:7]
	v_mfma_f32_16x16x32_bf16 v[60:63], v[168:171], v[218:221], v[60:63]
	v_mfma_f32_16x16x32_bf16 v[52:55], v[176:179], v[218:221], v[52:55]
	v_mfma_f32_16x16x32_bf16 v[44:47], v[168:171], v[226:229], v[44:47]
	v_mfma_f32_16x16x32_bf16 v[36:39], v[176:179], v[226:229], v[36:39]
	v_mfma_f32_16x16x32_bf16 v[28:31], v[168:171], v[234:237], v[28:31]
	v_mfma_f32_16x16x32_bf16 v[20:23], v[176:179], v[234:237], v[20:23]
	v_mfma_f32_16x16x32_bf16 v[12:15], v[168:171], v[242:245], v[12:15]
	v_mfma_f32_16x16x32_bf16 v[4:7], v[176:179], v[242:245], v[4:7]
	v_mfma_f32_16x16x32_bf16 v[56:59], v[180:183], v[214:217], v[56:59]
	v_mfma_f32_16x16x32_bf16 v[48:51], v[188:191], v[214:217], v[48:51]
	v_mfma_f32_16x16x32_bf16 v[40:43], v[180:183], v[222:225], v[40:43]
	v_mfma_f32_16x16x32_bf16 v[32:35], v[188:191], v[222:225], v[32:35]
	v_mfma_f32_16x16x32_bf16 v[24:27], v[180:183], v[230:233], v[24:27]
	v_mfma_f32_16x16x32_bf16 v[16:19], v[188:191], v[230:233], v[16:19]
	v_mfma_f32_16x16x32_bf16 v[8:11], v[180:183], v[238:241], v[8:11]
	v_mfma_f32_16x16x32_bf16 v[0:3], v[188:191], v[238:241], v[0:3]
	v_mfma_f32_16x16x32_bf16 v[56:59], v[184:187], v[218:221], v[56:59]
	v_mfma_f32_16x16x32_bf16 v[48:51], v[210:213], v[218:221], v[48:51]
	v_mfma_f32_16x16x32_bf16 v[40:43], v[184:187], v[226:229], v[40:43]
	v_mfma_f32_16x16x32_bf16 v[32:35], v[210:213], v[226:229], v[32:35]
	v_mfma_f32_16x16x32_bf16 v[24:27], v[184:187], v[234:237], v[24:27]
	v_mfma_f32_16x16x32_bf16 v[16:19], v[210:213], v[234:237], v[16:19]
	v_mfma_f32_16x16x32_bf16 v[8:11], v[184:187], v[242:245], v[8:11]
	v_mfma_f32_16x16x32_bf16 v[0:3], v[210:213], v[242:245], v[0:3]
	s_setprio 0
	s_barrier
; #define PG8_STAGE(bufoff, gbase, voff) do { _Pragma("unroll") for (int _i = 0; _i < 2; ++_i) \
;         __builtin_amdgcn_global_load_lds((const unsigned*)((const char*)(gbase) + (voff)[_i]), (PG8_LAS unsigned*)(lds + (bufoff) + ldsw + _i * 8192), 16, 0, 0); } while (0)
; #define PG8_LDA(dst, b, h) do { _Pragma("unroll") for (int m = 0; m < 4; ++m) _Pragma("unroll") for (int k = 0; k < 2; ++k) dst[m][k] = *(const PG8_LAS bf16x8*)(lds + PG8_SA(b, h) + aoff + m * 2048 + k * 1024); } while (0)
; #define PG8_LDB(dst, b, h) do { _Pragma("unroll") for (int n = 0; n < 2; ++n) _Pragma("unroll") for (int k = 0; k < 2; ++k) dst[n][k] = *(const PG8_LAS bf16x8*)(lds + PG8_SB(b, h) + boff + n * 2048 + k * 1024); } while (0)
; #define PG8_MMA(ai, bj, At, Bt) do { __builtin_amdgcn_s_setprio(1); _Pragma("unroll") for (int m = 0; m < 4; ++m) _Pragma("unroll") for (int n = 0; n < 2; ++n) _Pragma("unroll") for (int k = 0; k < 2; ++k) \
;         acc[ai][bj][m][n] = __builtin_amdgcn_mfma_f32_16x16x32_bf16(Bt[n][k], At[m][k], acc[ai][bj][m][n], 0, 0, 0); __builtin_amdgcn_s_setprio(0); } while (0)
; #define PG8_WAIT_V(n) asm volatile("s_waitcnt vmcnt(" #n ")" ::: "memory")
; #define PG8_WAIT_L(n) asm volatile("s_waitcnt lgkmcnt(" #n ")" ::: "memory")
; #define PG8_BAR __builtin_amdgcn_s_barrier()
; #define PG8_SCHED __builtin_amdgcn_sched_barrier(0)
; template <class Epi, class Sched, bool ALIGN_EPI = false, bool SP2 = false>
; __device__ __forceinline__ void gemm_phase(PG8_LAS unsigned char* lds, const Gemm g, const Sched& S, const Epi& E) {
;     ...
;             PG8_LDB(B0, 1, 0); PG8_LDB(B1, 1, 1); PG8_SCHED; PG8_LDA(At, 1, 0); PG8_STAGE(PG8_SA(0, 1), a2 + hstep, voffA);
;             PG8_WAIT_V(8); PG8_WAIT_L(0); PG8_BAR; PG8_MMA(0, 0, At, B0); PG8_MMA(0, 1, At, B1); PG8_BAR; PG8_SCHED;
;             PG8_LDA(At, 1, 1); PG8_STAGE(PG8_SB(1, 0), b3, voffB); PG8_STAGE(PG8_SB(1, 1), b3 + hstep, voffB); PG8_STAGE(PG8_SA(1, 0), a3, voffA);
;             PG8_WAIT_V(8); PG8_WAIT_L(0); PG8_BAR; PG8_MMA(1, 0, At, B0); PG8_MMA(1, 1, At, B1); PG8_BAR; PG8_SCHED;
;     ...
;         if constexpr (ALIGN_EPI) { if (wr == 0) PG8_BAR; }
	ds_read_b128 v[140:143], v254 offset:32768
	ds_read_b128 v[168:171], v254 offset:33792
	ds_read_b128 v[172:175], v254 offset:34816
	ds_read_b128 v[176:179], v254 offset:35840
	ds_read_b128 v[180:183], v254 offset:49152
	ds_read_b128 v[184:187], v254 offset:50176
	ds_read_b128 v[188:191], v254 offset:51200
	ds_read_b128 v[210:213], v254 offset:52224
	s_add_u32 s18, s18, 0x40000
	s_addc_u32 s19, s19, 0
	s_mov_b32 m0, s33
	ds_read_b128 v[214:217], v165 offset:32768
	ds_read_b128 v[218:221], v165 offset:33792
	ds_read_b128 v[222:225], v165 offset:34816
	ds_read_b128 v[226:229], v165 offset:35840
	ds_read_b128 v[230:233], v165 offset:36864
	ds_read_b128 v[234:237], v165 offset:37888
	ds_read_b128 v[238:241], v165 offset:38912
	ds_read_b128 v[242:245], v165 offset:39936
	global_load_lds_dwordx4 v134, s[18:19]
	s_mov_b32 m0, s34
	s_nop 0
	global_load_lds_dwordx4 v130, s[18:19]
	s_waitcnt vmcnt(8)
	s_waitcnt lgkmcnt(0)
	s_barrier
	s_setprio 1
	v_mfma_f32_16x16x32_bf16 v[124:127], v[140:143], v[214:217], v[124:127]
	v_mfma_f32_16x16x32_bf16 v[116:119], v[172:175], v[214:217], v[116:119]
	v_mfma_f32_16x16x32_bf16 v[108:111], v[140:143], v[222:225], v[108:111]
	v_mfma_f32_16x16x32_bf16 v[100:103], v[172:175], v[222:225], v[100:103]
	v_mfma_f32_16x16x32_bf16 v[92:95], v[140:143], v[230:233], v[92:95]
	v_mfma_f32_16x16x32_bf16 v[84:87], v[172:175], v[230:233], v[84:87]
	v_mfma_f32_16x16x32_bf16 v[76:79], v[140:143], v[238:241], v[76:79]
	v_mfma_f32_16x16x32_bf16 v[68:71], v[172:175], v[238:241], v[68:71]
	v_mfma_f32_16x16x32_bf16 v[124:127], v[168:171], v[218:221], v[124:127]
	v_mfma_f32_16x16x32_bf16 v[116:119], v[176:179], v[218:221], v[116:119]
	v_mfma_f32_16x16x32_bf16 v[108:111], v[168:171], v[226:229], v[108:111]
	v_mfma_f32_16x16x32_bf16 v[100:103], v[176:179], v[226:229], v[100:103]
	v_mfma_f32_16x16x32_bf16 v[92:95], v[168:171], v[234:237], v[92:95]
	v_mfma_f32_16x16x32_bf16 v[84:87], v[176:179], v[234:237], v[84:87]
	v_mfma_f32_16x16x32_bf16 v[76:79], v[168:171], v[242:245], v[76:79]
	v_mfma_f32_16x16x32_bf16 v[68:71], v[176:179], v[242:245], v[68:71]
	v_mfma_f32_16x16x32_bf16 v[120:123], v[180:183], v[214:217], v[120:123]
	v_mfma_f32_16x16x32_bf16 v[112:115], v[188:191], v[214:217], v[112:115]
	v_mfma_f32_16x16x32_bf16 v[104:107], v[180:183], v[222:225], v[104:107]
	v_mfma_f32_16x16x32_bf16 v[96:99], v[188:191], v[222:225], v[96:99]
	v_mfma_f32_16x16x32_bf16 v[88:91], v[180:183], v[230:233], v[88:91]
	v_mfma_f32_16x16x32_bf16 v[80:83], v[188:191], v[230:233], v[80:83]
	v_mfma_f32_16x16x32_bf16 v[72:75], v[180:183], v[238:241], v[72:75]
	v_mfma_f32_16x16x32_bf16 v[64:67], v[188:191], v[238:241], v[64:67]
	v_mfma_f32_16x16x32_bf16 v[120:123], v[184:187], v[218:221], v[120:123]
	v_mfma_f32_16x16x32_bf16 v[112:115], v[210:213], v[218:221], v[112:115]
	v_mfma_f32_16x16x32_bf16 v[104:107], v[184:187], v[226:229], v[104:107]
	v_mfma_f32_16x16x32_bf16 v[96:99], v[210:213], v[226:229], v[96:99]
	v_mfma_f32_16x16x32_bf16 v[88:91], v[184:187], v[234:237], v[88:91]
	v_mfma_f32_16x16x32_bf16 v[80:83], v[210:213], v[234:237], v[80:83]
	v_mfma_f32_16x16x32_bf16 v[72:75], v[184:187], v[242:245], v[72:75]
	v_mfma_f32_16x16x32_bf16 v[64:67], v[210:213], v[242:245], v[64:67]
	s_setprio 0
	s_barrier
	s_mov_b32 m0, s37
	s_add_u32 s16, s16, 0x40080
	s_addc_u32 s17, s17, 0
	ds_read_b128 v[214:217], v165 offset:49152
	ds_read_b128 v[218:221], v165 offset:50176
	ds_read_b128 v[222:225], v165 offset:51200
	ds_read_b128 v[226:229], v165 offset:52224
	ds_read_b128 v[230:233], v165 offset:53248
	ds_read_b128 v[234:237], v165 offset:54272
	ds_read_b128 v[238:241], v165 offset:55296
	ds_read_b128 v[242:245], v165 offset:56320
	s_add_u32 s98, s16, 0xfffc0000
	s_addc_u32 s99, s17, -1
	global_load_lds_dwordx4 v132, s[98:99] nt
	s_mov_b32 m0, s38
	s_nop 0
	global_load_lds_dwordx4 v128, s[98:99] nt
	s_mov_b32 m0, s41
	s_nop 0
	global_load_lds_dwordx4 v132, s[16:17] nt
	s_mov_b32 m0, s42
	s_nop 0
	global_load_lds_dwordx4 v128, s[16:17] nt
	s_mov_b32 m0, s39
	s_nop 0
	s_add_u32 s100, s18, 0xfffc0080
	s_addc_u32 s101, s19, -1
	global_load_lds_dwordx4 v134, s[100:101]
	s_mov_b32 m0, s40
	s_nop 0
	global_load_lds_dwordx4 v130, s[100:101]
	s_waitcnt vmcnt(8)
	s_waitcnt lgkmcnt(0)
	s_barrier
	s_setprio 1
	v_mfma_f32_16x16x32_bf16 v[60:63], v[140:143], v[214:217], v[60:63]
	v_mfma_f32_16x16x32_bf16 v[52:55], v[172:175], v[214:217], v[52:55]
	v_mfma_f32_16x16x32_bf16 v[44:47], v[140:143], v[222:225], v[44:47]
	v_mfma_f32_16x16x32_bf16 v[36:39], v[172:175], v[222:225], v[36:39]
	v_mfma_f32_16x16x32_bf16 v[28:31], v[140:143], v[230:233], v[28:31]
	v_mfma_f32_16x16x32_bf16 v[20:23], v[172:175], v[230:233], v[20:23]
	v_mfma_f32_16x16x32_bf16 v[12:15], v[140:143], v[238:241], v[12:15]
	v_mfma_f32_16x16x32_bf16 v[4:7], v[172:175], v[238:241], v[4:7]
	v_mfma_f32_16x16x32_bf16 v[60:63], v[168:171], v[218:221], v[60:63]
	v_mfma_f32_16x16x32_bf16 v[52:55], v[176:179], v[218:221], v[52:55]
	v_mfma_f32_16x16x32_bf16 v[44:47], v[168:171], v[226:229], v[44:47]
	v_mfma_f32_16x16x32_bf16 v[36:39], v[176:179], v[226:229], v[36:39]
	v_mfma_f32_16x16x32_bf16 v[28:31], v[168:171], v[234:237], v[28:31]
	v_mfma_f32_16x16x32_bf16 v[20:23], v[176:179], v[234:237], v[20:23]
	v_mfma_f32_16x16x32_bf16 v[12:15], v[168:171], v[242:245], v[12:15]
	v_mfma_f32_16x16x32_bf16 v[4:7], v[176:179], v[242:245], v[4:7]
	v_mfma_f32_16x16x32_bf16 v[56:59], v[180:183], v[214:217], v[56:59]
	v_mfma_f32_16x16x32_bf16 v[48:51], v[188:191], v[214:217], v[48:51]
	v_mfma_f32_16x16x32_bf16 v[40:43], v[180:183], v[222:225], v[40:43]
	v_mfma_f32_16x16x32_bf16 v[32:35], v[188:191], v[222:225], v[32:35]
	v_mfma_f32_16x16x32_bf16 v[24:27], v[180:183], v[230:233], v[24:27]
	v_mfma_f32_16x16x32_bf16 v[16:19], v[188:191], v[230:233], v[16:19]
	v_mfma_f32_16x16x32_bf16 v[8:11], v[180:183], v[238:241], v[8:11]
	v_mfma_f32_16x16x32_bf16 v[0:3], v[188:191], v[238:241], v[0:3]
	v_mfma_f32_16x16x32_bf16 v[56:59], v[184:187], v[218:221], v[56:59]
	v_mfma_f32_16x16x32_bf16 v[48:51], v[210:213], v[218:221], v[48:51]
	v_mfma_f32_16x16x32_bf16 v[40:43], v[184:187], v[226:229], v[40:43]
	v_mfma_f32_16x16x32_bf16 v[32:35], v[210:213], v[226:229], v[32:35]
	v_mfma_f32_16x16x32_bf16 v[24:27], v[184:187], v[234:237], v[24:27]
	v_mfma_f32_16x16x32_bf16 v[16:19], v[210:213], v[234:237], v[16:19]
	v_mfma_f32_16x16x32_bf16 v[8:11], v[184:187], v[242:245], v[8:11]
	v_mfma_f32_16x16x32_bf16 v[0:3], v[210:213], v[242:245], v[0:3]
	s_setprio 0
	s_barrier
	s_add_i32 s53, s53, 2
	s_add_u32 s14, s14, 0x100
	s_addc_u32 s15, s15, 0
	s_add_u32 s51, s51, 0x100
	s_addc_u32 s52, s52, 0
	s_cmp_gt_u32 s53, 13
	s_cbranch_scc0 .LBB0_446
	s_and_b64 vcc, exec, s[2:3]
	s_cbranch_vccz .LBB0_449
	s_barrier
